# GEMM K-loops: back edge rotated (counter/pointer updates and next head's SALU moved in front of the loop-closing barrier; branch lands on the first load-segment instruction)
# baseline (speedup 1.0000x reference)
.LBB0_94:
	s_add_u32 s60, s48, 0xfffc0080
	s_addc_u32 s61, s49, -1
	s_add_i32 s88, 0, 0x10000
	s_cmp_eq_u32 s87, 12
	s_cselect_b32 vcc_hi, s59, s61
	s_cselect_b32 vcc_lo, s83, s60
	s_cselect_b32 s61, s95, s86
	s_cselect_b32 s60, s84, s85
	s_add_i32 s90, 0, 0x14000
.Lk1_rot:
	s_add_u32 s100, s48, 0xfffc0000
	s_addc_u32 s101, s49, -1
	v_lshl_add_u64 v[198:199], s[100:101], 0, v[152:153]
	s_mov_b32 m0, s77
	s_nop 0
	global_load_lds_dwordx4 v[198:199], off
	v_lshl_add_u64 v[198:199], s[100:101], 0, v[148:149]
	s_mov_b32 m0, s78
	s_nop 0
	global_load_lds_dwordx4 v[198:199], off


	v_add_u32_e32 v2, s88, v182


	ds_read_b128 v[132:135], v2
	ds_read_b128 v[136:139], v2 offset:1024
	ds_read_b128 v[140:143], v2 offset:2048
	ds_read_b128 v[144:147], v2 offset:3072
	v_add_u32_e32 v2, s90, v182
	ds_read_b128 v[162:165], v2
	ds_read_b128 v[166:169], v2 offset:1024
	ds_read_b128 v[170:173], v2 offset:2048
	ds_read_b128 v[174:177], v2 offset:3072
	v_lshl_add_u64 v[198:199], s[48:49], 0, v[158:159]
	s_add_i32 m0, s73, 0xc000
	ds_read_b128 v[178:181], v185
	ds_read_b128 v[186:189], v185 offset:1024
	ds_read_b128 v[190:193], v185 offset:2048
	ds_read_b128 v[194:197], v185 offset:3072
	ds_read_b128 v[208:211], v185 offset:4096
	ds_read_b128 v[212:215], v185 offset:5120
	ds_read_b128 v[216:219], v185 offset:6144
	ds_read_b128 v[220:223], v185 offset:7168
	global_load_lds_dwordx4 v[198:199], off
	v_lshl_add_u64 v[198:199], s[48:49], 0, v[160:161]
	s_add_i32 m0, s73, 0xe000
	s_nop 0
	global_load_lds_dwordx4 v[198:199], off
	s_waitcnt vmcnt(8)
	s_waitcnt lgkmcnt(0)
	s_barrier

	s_waitcnt lgkmcnt(0)
	v_mfma_f32_16x16x32_bf16 v[128:131], v[132:135], v[178:181], v[128:131]
	v_mfma_f32_16x16x32_bf16 v[120:123], v[140:143], v[178:181], v[120:123]
	v_mfma_f32_16x16x32_bf16 v[112:115], v[132:135], v[190:193], v[112:115]
	v_mfma_f32_16x16x32_bf16 v[84:87], v[140:143], v[190:193], v[84:87]
	v_mfma_f32_16x16x32_bf16 v[104:107], v[132:135], v[208:211], v[104:107]
	v_mfma_f32_16x16x32_bf16 v[72:75], v[140:143], v[208:211], v[72:75]
	v_mfma_f32_16x16x32_bf16 v[96:99], v[132:135], v[216:219], v[96:99]
	v_mfma_f32_16x16x32_bf16 v[88:91], v[140:143], v[216:219], v[88:91]
	v_mfma_f32_16x16x32_bf16 v[128:131], v[136:139], v[186:189], v[128:131]
	v_mfma_f32_16x16x32_bf16 v[120:123], v[144:147], v[186:189], v[120:123]
	v_mfma_f32_16x16x32_bf16 v[112:115], v[136:139], v[194:197], v[112:115]
	v_mfma_f32_16x16x32_bf16 v[84:87], v[144:147], v[194:197], v[84:87]
	v_mfma_f32_16x16x32_bf16 v[104:107], v[136:139], v[212:215], v[104:107]
	v_mfma_f32_16x16x32_bf16 v[72:75], v[144:147], v[212:215], v[72:75]
	v_mfma_f32_16x16x32_bf16 v[96:99], v[136:139], v[220:223], v[96:99]
	v_mfma_f32_16x16x32_bf16 v[88:91], v[144:147], v[220:223], v[88:91]


	v_mfma_f32_16x16x32_bf16 v[124:127], v[162:165], v[178:181], v[124:127]
	v_mfma_f32_16x16x32_bf16 v[116:119], v[170:173], v[178:181], v[116:119]
	v_mfma_f32_16x16x32_bf16 v[108:111], v[162:165], v[190:193], v[108:111]
	v_mfma_f32_16x16x32_bf16 v[76:79], v[170:173], v[190:193], v[76:79]
	v_mfma_f32_16x16x32_bf16 v[100:103], v[162:165], v[208:211], v[100:103]
	v_mfma_f32_16x16x32_bf16 v[68:71], v[170:173], v[208:211], v[68:71]
	v_mfma_f32_16x16x32_bf16 v[92:95], v[162:165], v[216:219], v[92:95]
	v_mfma_f32_16x16x32_bf16 v[80:83], v[170:173], v[216:219], v[80:83]
	v_mfma_f32_16x16x32_bf16 v[124:127], v[166:169], v[186:189], v[124:127]
	v_mfma_f32_16x16x32_bf16 v[116:119], v[174:177], v[186:189], v[116:119]
	v_mfma_f32_16x16x32_bf16 v[108:111], v[166:169], v[194:197], v[108:111]
	v_mfma_f32_16x16x32_bf16 v[76:79], v[174:177], v[194:197], v[76:79]
	v_mfma_f32_16x16x32_bf16 v[100:103], v[166:169], v[212:215], v[100:103]
	v_mfma_f32_16x16x32_bf16 v[68:71], v[174:177], v[212:215], v[68:71]
	v_mfma_f32_16x16x32_bf16 v[92:95], v[166:169], v[220:223], v[92:95]
	v_mfma_f32_16x16x32_bf16 v[80:83], v[174:177], v[220:223], v[80:83]

	s_barrier
	s_add_i32 s88, s88, s72
	v_lshl_add_u64 v[198:199], s[60:61], 0, v[150:151]
	s_mov_b32 m0, s88
	ds_read_b128 v[178:181], v185 offset:16384
	ds_read_b128 v[186:189], v185 offset:17408
	ds_read_b128 v[190:193], v185 offset:18432
	ds_read_b128 v[194:197], v185 offset:19456
	ds_read_b128 v[208:211], v185 offset:20480
	ds_read_b128 v[212:215], v185 offset:21504
	ds_read_b128 v[216:219], v185 offset:22528
	ds_read_b128 v[220:223], v185 offset:23552
	global_load_lds_dwordx4 v[198:199], off
	s_add_i32 m0, s88, 0x2000
	s_add_u32 s88, s60, 0x40000
	v_lshl_add_u64 v[204:205], s[60:61], 0, v[0:1]
	s_addc_u32 s89, s61, 0
	s_add_i32 s90, s90, s72
	global_load_lds_dwordx4 v[204:205], off
	v_lshl_add_u64 v[206:207], s[88:89], 0, v[150:151]
	s_mov_b32 m0, s90
	v_lshl_add_u64 v[224:225], vcc, 0, v[148:149]
	global_load_lds_dwordx4 v[206:207], off
	v_lshl_add_u64 v[206:207], s[88:89], 0, v[0:1]
	s_add_i32 m0, s90, 0x2000
	s_nop 0
	global_load_lds_dwordx4 v[206:207], off
	v_lshl_add_u64 v[206:207], vcc, 0, v[152:153]


	s_waitcnt vmcnt(6)
	s_waitcnt lgkmcnt(0)
	s_barrier

	s_waitcnt lgkmcnt(0)
	v_mfma_f32_16x16x32_bf16 v[64:67], v[132:135], v[178:181], v[64:67]
	v_mfma_f32_16x16x32_bf16 v[56:59], v[140:143], v[178:181], v[56:59]
	v_mfma_f32_16x16x32_bf16 v[52:55], v[132:135], v[190:193], v[52:55]
	v_mfma_f32_16x16x32_bf16 v[20:23], v[140:143], v[190:193], v[20:23]
	v_mfma_f32_16x16x32_bf16 v[40:43], v[132:135], v[208:211], v[40:43]
	v_mfma_f32_16x16x32_bf16 v[8:11], v[140:143], v[208:211], v[8:11]
	v_mfma_f32_16x16x32_bf16 v[32:35], v[132:135], v[216:219], v[32:35]
	v_mfma_f32_16x16x32_bf16 v[24:27], v[140:143], v[216:219], v[24:27]
	v_mfma_f32_16x16x32_bf16 v[64:67], v[136:139], v[186:189], v[64:67]
	v_mfma_f32_16x16x32_bf16 v[56:59], v[144:147], v[186:189], v[56:59]
	v_mfma_f32_16x16x32_bf16 v[52:55], v[136:139], v[194:197], v[52:55]
	v_mfma_f32_16x16x32_bf16 v[20:23], v[144:147], v[194:197], v[20:23]
	v_mfma_f32_16x16x32_bf16 v[40:43], v[136:139], v[212:215], v[40:43]
	v_mfma_f32_16x16x32_bf16 v[8:11], v[144:147], v[212:215], v[8:11]
	v_mfma_f32_16x16x32_bf16 v[32:35], v[136:139], v[220:223], v[32:35]
	v_mfma_f32_16x16x32_bf16 v[24:27], v[144:147], v[220:223], v[24:27]


	v_mfma_f32_16x16x32_bf16 v[60:63], v[162:165], v[178:181], v[60:63]
	v_mfma_f32_16x16x32_bf16 v[48:51], v[170:173], v[178:181], v[48:51]
	v_mfma_f32_16x16x32_bf16 v[44:47], v[162:165], v[190:193], v[44:47]
	v_mfma_f32_16x16x32_bf16 v[12:15], v[170:173], v[190:193], v[12:15]
	v_mfma_f32_16x16x32_bf16 v[36:39], v[162:165], v[208:211], v[36:39]
	v_mfma_f32_16x16x32_bf16 v[4:7], v[170:173], v[208:211], v[4:7]
	v_mfma_f32_16x16x32_bf16 v[28:31], v[162:165], v[216:219], v[28:31]
	v_mfma_f32_16x16x32_bf16 v[16:19], v[170:173], v[216:219], v[16:19]
	v_mfma_f32_16x16x32_bf16 v[60:63], v[166:169], v[186:189], v[60:63]
	v_mfma_f32_16x16x32_bf16 v[48:51], v[174:177], v[186:189], v[48:51]
	v_mfma_f32_16x16x32_bf16 v[44:47], v[166:169], v[194:197], v[44:47]
	v_mfma_f32_16x16x32_bf16 v[12:15], v[174:177], v[194:197], v[12:15]
	v_mfma_f32_16x16x32_bf16 v[36:39], v[166:169], v[212:215], v[36:39]
	v_mfma_f32_16x16x32_bf16 v[4:7], v[174:177], v[212:215], v[4:7]
	v_mfma_f32_16x16x32_bf16 v[28:31], v[166:169], v[220:223], v[28:31]
	v_mfma_f32_16x16x32_bf16 v[16:19], v[174:177], v[220:223], v[16:19]

	s_barrier
	s_add_i32 s90, 0, 0x18000
	v_add_u32_e32 v2, s90, v182
	s_add_i32 s91, 0, 0x1c000
	ds_read_b128 v[132:135], v2
	ds_read_b128 v[136:139], v2 offset:1024
	ds_read_b128 v[140:143], v2 offset:2048
	ds_read_b128 v[144:147], v2 offset:3072
	v_add_u32_e32 v2, s91, v182
	ds_read_b128 v[162:165], v2
	ds_read_b128 v[166:169], v2 offset:1024
	ds_read_b128 v[170:173], v2 offset:2048
	ds_read_b128 v[174:177], v2 offset:3072
	s_add_u32 s88, vcc_lo, 0x40000
	s_addc_u32 s89, vcc_hi, 0
	s_mov_b32 m0, s73
	s_nop 0
	global_load_lds_dwordx4 v[206:207], off
	s_mov_b32 m0, s74
	s_nop 0
	global_load_lds_dwordx4 v[224:225], off
	s_mov_b32 m0, s75
	v_lshl_add_u64 v[226:227], s[88:89], 0, v[152:153]
	ds_read_b128 v[178:181], v185 offset:32768
	ds_read_b128 v[186:189], v185 offset:33792
	ds_read_b128 v[190:193], v185 offset:34816
	ds_read_b128 v[194:197], v185 offset:35840
	ds_read_b128 v[208:211], v185 offset:36864
	ds_read_b128 v[212:215], v185 offset:37888
	ds_read_b128 v[216:219], v185 offset:38912
	ds_read_b128 v[220:223], v185 offset:39936
	global_load_lds_dwordx4 v[226:227], off
	v_lshl_add_u64 v[226:227], s[88:89], 0, v[148:149]
	s_mov_b32 m0, s76
	s_nop 0
	global_load_lds_dwordx4 v[226:227], off
	s_waitcnt vmcnt(8)
	s_waitcnt lgkmcnt(0)
	s_barrier

	s_waitcnt lgkmcnt(0)
	v_mfma_f32_16x16x32_bf16 v[128:131], v[132:135], v[178:181], v[128:131]
	v_mfma_f32_16x16x32_bf16 v[120:123], v[140:143], v[178:181], v[120:123]
	v_mfma_f32_16x16x32_bf16 v[112:115], v[132:135], v[190:193], v[112:115]
	v_mfma_f32_16x16x32_bf16 v[84:87], v[140:143], v[190:193], v[84:87]
	v_mfma_f32_16x16x32_bf16 v[104:107], v[132:135], v[208:211], v[104:107]
	v_mfma_f32_16x16x32_bf16 v[72:75], v[140:143], v[208:211], v[72:75]
	v_mfma_f32_16x16x32_bf16 v[96:99], v[132:135], v[216:219], v[96:99]
	v_mfma_f32_16x16x32_bf16 v[88:91], v[140:143], v[216:219], v[88:91]
	v_mfma_f32_16x16x32_bf16 v[128:131], v[136:139], v[186:189], v[128:131]
	v_mfma_f32_16x16x32_bf16 v[120:123], v[144:147], v[186:189], v[120:123]
	v_mfma_f32_16x16x32_bf16 v[112:115], v[136:139], v[194:197], v[112:115]
	v_mfma_f32_16x16x32_bf16 v[84:87], v[144:147], v[194:197], v[84:87]
	v_mfma_f32_16x16x32_bf16 v[104:107], v[136:139], v[212:215], v[104:107]
	v_mfma_f32_16x16x32_bf16 v[72:75], v[144:147], v[212:215], v[72:75]
	v_mfma_f32_16x16x32_bf16 v[96:99], v[136:139], v[220:223], v[96:99]
	v_mfma_f32_16x16x32_bf16 v[88:91], v[144:147], v[220:223], v[88:91]


	v_mfma_f32_16x16x32_bf16 v[124:127], v[162:165], v[178:181], v[124:127]
	v_mfma_f32_16x16x32_bf16 v[116:119], v[170:173], v[178:181], v[116:119]
	v_mfma_f32_16x16x32_bf16 v[108:111], v[162:165], v[190:193], v[108:111]
	v_mfma_f32_16x16x32_bf16 v[76:79], v[170:173], v[190:193], v[76:79]
	v_mfma_f32_16x16x32_bf16 v[100:103], v[162:165], v[208:211], v[100:103]
	v_mfma_f32_16x16x32_bf16 v[68:71], v[170:173], v[208:211], v[68:71]
	v_mfma_f32_16x16x32_bf16 v[92:95], v[162:165], v[216:219], v[92:95]
	v_mfma_f32_16x16x32_bf16 v[80:83], v[170:173], v[216:219], v[80:83]
	v_mfma_f32_16x16x32_bf16 v[124:127], v[166:169], v[186:189], v[124:127]
	v_mfma_f32_16x16x32_bf16 v[116:119], v[174:177], v[186:189], v[116:119]
	v_mfma_f32_16x16x32_bf16 v[108:111], v[166:169], v[194:197], v[108:111]
	v_mfma_f32_16x16x32_bf16 v[76:79], v[174:177], v[194:197], v[76:79]
	v_mfma_f32_16x16x32_bf16 v[100:103], v[166:169], v[212:215], v[100:103]
	v_mfma_f32_16x16x32_bf16 v[68:71], v[174:177], v[212:215], v[68:71]
	v_mfma_f32_16x16x32_bf16 v[92:95], v[166:169], v[220:223], v[92:95]
	v_mfma_f32_16x16x32_bf16 v[80:83], v[174:177], v[220:223], v[80:83]

	s_barrier
	s_add_i32 s88, s90, s72
	v_lshl_add_u64 v[198:199], v[198:199], 0, s[12:13]
	s_mov_b32 m0, s88
	ds_read_b128 v[178:181], v185 offset:49152
	ds_read_b128 v[186:189], v185 offset:50176
	ds_read_b128 v[190:193], v185 offset:51200
	ds_read_b128 v[194:197], v185 offset:52224
	ds_read_b128 v[208:211], v185 offset:53248
	ds_read_b128 v[212:215], v185 offset:54272
	ds_read_b128 v[216:219], v185 offset:55296
	ds_read_b128 v[220:223], v185 offset:56320
	global_load_lds_dwordx4 v[198:199], off
	s_add_i32 m0, s88, 0x2000
	s_add_u32 s60, s60, 0x40080
	v_lshl_add_u64 v[198:199], v[204:205], 0, s[12:13]
	s_addc_u32 s61, s61, 0
	s_add_i32 s88, s91, s72
	global_load_lds_dwordx4 v[198:199], off
	v_lshl_add_u64 v[198:199], s[60:61], 0, v[150:151]
	s_mov_b32 m0, s88
	s_nop 0
	global_load_lds_dwordx4 v[198:199], off
	v_lshl_add_u64 v[198:199], s[60:61], 0, v[0:1]
	s_add_i32 m0, s88, 0x2000
	s_nop 0
	global_load_lds_dwordx4 v[198:199], off


	s_waitcnt vmcnt(6)
	s_waitcnt lgkmcnt(0)
	s_barrier

	s_waitcnt lgkmcnt(0)
	v_mfma_f32_16x16x32_bf16 v[64:67], v[132:135], v[178:181], v[64:67]
	v_mfma_f32_16x16x32_bf16 v[56:59], v[140:143], v[178:181], v[56:59]
	v_mfma_f32_16x16x32_bf16 v[52:55], v[132:135], v[190:193], v[52:55]
	v_mfma_f32_16x16x32_bf16 v[20:23], v[140:143], v[190:193], v[20:23]
	v_mfma_f32_16x16x32_bf16 v[40:43], v[132:135], v[208:211], v[40:43]
	v_mfma_f32_16x16x32_bf16 v[8:11], v[140:143], v[208:211], v[8:11]
	v_mfma_f32_16x16x32_bf16 v[32:35], v[132:135], v[216:219], v[32:35]
	v_mfma_f32_16x16x32_bf16 v[24:27], v[140:143], v[216:219], v[24:27]
	v_mfma_f32_16x16x32_bf16 v[64:67], v[136:139], v[186:189], v[64:67]
	v_mfma_f32_16x16x32_bf16 v[56:59], v[144:147], v[186:189], v[56:59]
	v_mfma_f32_16x16x32_bf16 v[52:55], v[136:139], v[194:197], v[52:55]
	v_mfma_f32_16x16x32_bf16 v[20:23], v[144:147], v[194:197], v[20:23]
	v_mfma_f32_16x16x32_bf16 v[40:43], v[136:139], v[212:215], v[40:43]
	v_mfma_f32_16x16x32_bf16 v[8:11], v[144:147], v[212:215], v[8:11]
	v_mfma_f32_16x16x32_bf16 v[32:35], v[136:139], v[220:223], v[32:35]
	v_mfma_f32_16x16x32_bf16 v[24:27], v[144:147], v[220:223], v[24:27]


	v_mfma_f32_16x16x32_bf16 v[60:63], v[162:165], v[178:181], v[60:63]
	v_mfma_f32_16x16x32_bf16 v[48:51], v[170:173], v[178:181], v[48:51]
	v_mfma_f32_16x16x32_bf16 v[44:47], v[162:165], v[190:193], v[44:47]
	v_mfma_f32_16x16x32_bf16 v[12:15], v[170:173], v[190:193], v[12:15]
	v_mfma_f32_16x16x32_bf16 v[36:39], v[162:165], v[208:211], v[36:39]
	v_mfma_f32_16x16x32_bf16 v[4:7], v[170:173], v[208:211], v[4:7]
	v_mfma_f32_16x16x32_bf16 v[28:31], v[162:165], v[216:219], v[28:31]
	v_mfma_f32_16x16x32_bf16 v[16:19], v[170:173], v[216:219], v[16:19]
	v_mfma_f32_16x16x32_bf16 v[60:63], v[166:169], v[186:189], v[60:63]
	v_mfma_f32_16x16x32_bf16 v[48:51], v[174:177], v[186:189], v[48:51]
	v_mfma_f32_16x16x32_bf16 v[44:47], v[166:169], v[194:197], v[44:47]
	v_mfma_f32_16x16x32_bf16 v[12:15], v[174:177], v[194:197], v[12:15]
	v_mfma_f32_16x16x32_bf16 v[36:39], v[166:169], v[212:215], v[36:39]
	v_mfma_f32_16x16x32_bf16 v[4:7], v[174:177], v[212:215], v[4:7]
	v_mfma_f32_16x16x32_bf16 v[28:31], v[166:169], v[220:223], v[28:31]
	v_mfma_f32_16x16x32_bf16 v[16:19], v[174:177], v[220:223], v[16:19]

	s_add_i32 s87, s87, 2
	s_add_u32 s48, s48, 0x100
	s_addc_u32 s49, s49, 0
	s_add_u32 s85, s85, 0x100
	s_addc_u32 s86, s86, 0
	s_add_u32 s60, s48, 0xfffc0080
	s_addc_u32 s61, s49, -1
	s_add_i32 s88, 0, 0x10000
	s_cmp_eq_u32 s87, 12
	s_cselect_b32 vcc_hi, s59, s61
	s_cselect_b32 vcc_lo, s83, s60
	s_cselect_b32 s61, s95, s86
	s_cselect_b32 s60, s84, s85
	s_add_i32 s90, 0, 0x14000
	s_cmp_gt_u32 s87, 13
	s_barrier
	s_cbranch_scc0 .Lk1_rot


	s_and_b64 vcc, exec, s[20:21]
	s_cbranch_vccz .LBB0_97
	s_barrier

.LBB0_685:
	s_add_u32 s48, s46, 0xfff80080
	s_addc_u32 s49, s47, -1
	s_add_i32 s81, 0, 0x10000
	s_cmp_eq_u32 s80, 28
	s_cselect_b32 s51, s35, s49
	s_cselect_b32 s50, s76, s48
	s_cselect_b32 s49, s21, s79
	s_cselect_b32 s48, s77, s78
	s_add_i32 s84, 0, 0x14000
.Lk2_rot:
	s_add_u32 s82, s46, 0xfff80000
	s_addc_u32 s83, s47, -1
	v_lshl_add_u64 v[200:201], s[82:83], 0, v[134:135]
	s_mov_b32 m0, s71
	s_nop 0
	global_load_lds_dwordx4 v[200:201], off
	v_lshl_add_u64 v[200:201], s[82:83], 0, v[132:133]
	s_mov_b32 m0, s72
	s_nop 0
	global_load_lds_dwordx4 v[200:201], off


	v_add_u32_e32 v156, s81, v149
	v_add_u32_e32 v172, s84, v149
	ds_read_b128 v[140:143], v156
	ds_read_b128 v[144:147], v156 offset:1024
	ds_read_b128 v[152:155], v156 offset:2048
	ds_read_b128 v[156:159], v156 offset:3072
	ds_read_b128 v[160:163], v172
	ds_read_b128 v[164:167], v172 offset:1024
	ds_read_b128 v[168:171], v172 offset:2048
	ds_read_b128 v[172:175], v172 offset:3072
	v_lshl_add_u64 v[200:201], s[46:47], 0, v[136:137]
	s_add_i32 m0, s59, 0xc000
	ds_read_b128 v[176:179], v151
	ds_read_b128 v[180:183], v151 offset:1024
	ds_read_b128 v[184:187], v151 offset:2048
	ds_read_b128 v[188:191], v151 offset:3072
	ds_read_b128 v[192:195], v151 offset:4096
	ds_read_b128 v[196:199], v151 offset:5120
	ds_read_b128 v[204:207], v151 offset:6144
	ds_read_b128 v[208:211], v151 offset:7168
	global_load_lds_dwordx4 v[200:201], off
	v_lshl_add_u64 v[200:201], s[46:47], 0, v[138:139]
	s_add_i32 m0, s59, 0xe000
	s_nop 0
	global_load_lds_dwordx4 v[200:201], off
	s_waitcnt vmcnt(8)
	s_waitcnt lgkmcnt(0)
	s_barrier

	s_waitcnt lgkmcnt(0)
	v_mfma_f32_16x16x32_bf16 v[128:131], v[140:143], v[176:179], v[128:131]
	v_mfma_f32_16x16x32_bf16 v[124:127], v[152:155], v[176:179], v[124:127]
	v_mfma_f32_16x16x32_bf16 v[112:115], v[140:143], v[184:187], v[112:115]
	v_mfma_f32_16x16x32_bf16 v[108:111], v[152:155], v[184:187], v[108:111]
	v_mfma_f32_16x16x32_bf16 v[96:99], v[140:143], v[192:195], v[96:99]
	v_mfma_f32_16x16x32_bf16 v[92:95], v[152:155], v[192:195], v[92:95]
	v_mfma_f32_16x16x32_bf16 v[80:83], v[140:143], v[204:207], v[80:83]
	v_mfma_f32_16x16x32_bf16 v[76:79], v[152:155], v[204:207], v[76:79]
	v_mfma_f32_16x16x32_bf16 v[128:131], v[144:147], v[180:183], v[128:131]
	v_mfma_f32_16x16x32_bf16 v[124:127], v[156:159], v[180:183], v[124:127]
	v_mfma_f32_16x16x32_bf16 v[112:115], v[144:147], v[188:191], v[112:115]
	v_mfma_f32_16x16x32_bf16 v[108:111], v[156:159], v[188:191], v[108:111]
	v_mfma_f32_16x16x32_bf16 v[96:99], v[144:147], v[196:199], v[96:99]
	v_mfma_f32_16x16x32_bf16 v[92:95], v[156:159], v[196:199], v[92:95]
	v_mfma_f32_16x16x32_bf16 v[80:83], v[144:147], v[208:211], v[80:83]
	v_mfma_f32_16x16x32_bf16 v[76:79], v[156:159], v[208:211], v[76:79]


	v_mfma_f32_16x16x32_bf16 v[120:123], v[160:163], v[176:179], v[120:123]
	v_mfma_f32_16x16x32_bf16 v[116:119], v[168:171], v[176:179], v[116:119]
	v_mfma_f32_16x16x32_bf16 v[104:107], v[160:163], v[184:187], v[104:107]
	v_mfma_f32_16x16x32_bf16 v[100:103], v[168:171], v[184:187], v[100:103]
	v_mfma_f32_16x16x32_bf16 v[88:91], v[160:163], v[192:195], v[88:91]
	v_mfma_f32_16x16x32_bf16 v[84:87], v[168:171], v[192:195], v[84:87]
	v_mfma_f32_16x16x32_bf16 v[72:75], v[160:163], v[204:207], v[72:75]
	v_mfma_f32_16x16x32_bf16 v[68:71], v[168:171], v[204:207], v[68:71]
	v_mfma_f32_16x16x32_bf16 v[120:123], v[164:167], v[180:183], v[120:123]
	v_mfma_f32_16x16x32_bf16 v[116:119], v[172:175], v[180:183], v[116:119]
	v_mfma_f32_16x16x32_bf16 v[104:107], v[164:167], v[188:191], v[104:107]
	v_mfma_f32_16x16x32_bf16 v[100:103], v[172:175], v[188:191], v[100:103]
	v_mfma_f32_16x16x32_bf16 v[88:91], v[164:167], v[196:199], v[88:91]
	v_mfma_f32_16x16x32_bf16 v[84:87], v[172:175], v[196:199], v[84:87]
	v_mfma_f32_16x16x32_bf16 v[72:75], v[164:167], v[208:211], v[72:75]
	v_mfma_f32_16x16x32_bf16 v[68:71], v[172:175], v[208:211], v[68:71]

	s_barrier
	s_add_i32 s81, s81, s52
	v_lshl_add_u64 v[200:201], s[48:49], 0, v[2:3]
	s_mov_b32 m0, s81
	ds_read_b128 v[176:179], v151 offset:16384
	ds_read_b128 v[180:183], v151 offset:17408
	ds_read_b128 v[184:187], v151 offset:18432
	ds_read_b128 v[188:191], v151 offset:19456
	ds_read_b128 v[192:195], v151 offset:20480
	ds_read_b128 v[196:199], v151 offset:21504
	ds_read_b128 v[204:207], v151 offset:22528
	ds_read_b128 v[208:211], v151 offset:23552
	global_load_lds_dwordx4 v[200:201], off
	s_add_i32 m0, s81, 0x2000
	s_add_u32 s82, s48, 0x80000
	v_lshl_add_u64 v[212:213], s[48:49], 0, v[0:1]
	s_addc_u32 s83, s49, 0
	s_add_i32 s81, s84, s52
	global_load_lds_dwordx4 v[212:213], off
	v_lshl_add_u64 v[214:215], s[82:83], 0, v[2:3]
	s_mov_b32 m0, s81
	v_lshl_add_u64 v[216:217], s[50:51], 0, v[132:133]
	global_load_lds_dwordx4 v[214:215], off
	v_lshl_add_u64 v[214:215], s[82:83], 0, v[0:1]
	s_add_i32 m0, s81, 0x2000
	s_nop 0
	global_load_lds_dwordx4 v[214:215], off
	v_lshl_add_u64 v[214:215], s[50:51], 0, v[134:135]


	s_waitcnt vmcnt(6)
	s_waitcnt lgkmcnt(0)
	s_barrier

	s_waitcnt lgkmcnt(0)
	v_mfma_f32_16x16x32_bf16 v[64:67], v[140:143], v[176:179], v[64:67]
	v_mfma_f32_16x16x32_bf16 v[60:63], v[152:155], v[176:179], v[60:63]
	v_mfma_f32_16x16x32_bf16 v[48:51], v[140:143], v[184:187], v[48:51]
	v_mfma_f32_16x16x32_bf16 v[44:47], v[152:155], v[184:187], v[44:47]
	v_mfma_f32_16x16x32_bf16 v[32:35], v[140:143], v[192:195], v[32:35]
	v_mfma_f32_16x16x32_bf16 v[28:31], v[152:155], v[192:195], v[28:31]
	v_mfma_f32_16x16x32_bf16 v[16:19], v[140:143], v[204:207], v[16:19]
	v_mfma_f32_16x16x32_bf16 v[12:15], v[152:155], v[204:207], v[12:15]
	v_mfma_f32_16x16x32_bf16 v[64:67], v[144:147], v[180:183], v[64:67]
	v_mfma_f32_16x16x32_bf16 v[60:63], v[156:159], v[180:183], v[60:63]
	v_mfma_f32_16x16x32_bf16 v[48:51], v[144:147], v[188:191], v[48:51]
	v_mfma_f32_16x16x32_bf16 v[44:47], v[156:159], v[188:191], v[44:47]
	v_mfma_f32_16x16x32_bf16 v[32:35], v[144:147], v[196:199], v[32:35]
	v_mfma_f32_16x16x32_bf16 v[28:31], v[156:159], v[196:199], v[28:31]
	v_mfma_f32_16x16x32_bf16 v[16:19], v[144:147], v[208:211], v[16:19]
	v_mfma_f32_16x16x32_bf16 v[12:15], v[156:159], v[208:211], v[12:15]


	v_mfma_f32_16x16x32_bf16 v[56:59], v[160:163], v[176:179], v[56:59]
	v_mfma_f32_16x16x32_bf16 v[52:55], v[168:171], v[176:179], v[52:55]
	v_mfma_f32_16x16x32_bf16 v[40:43], v[160:163], v[184:187], v[40:43]
	v_mfma_f32_16x16x32_bf16 v[36:39], v[168:171], v[184:187], v[36:39]
	v_mfma_f32_16x16x32_bf16 v[24:27], v[160:163], v[192:195], v[24:27]
	v_mfma_f32_16x16x32_bf16 v[20:23], v[168:171], v[192:195], v[20:23]
	v_mfma_f32_16x16x32_bf16 v[8:11], v[160:163], v[204:207], v[8:11]
	v_mfma_f32_16x16x32_bf16 v[4:7], v[168:171], v[204:207], v[4:7]
	v_mfma_f32_16x16x32_bf16 v[56:59], v[164:167], v[180:183], v[56:59]
	v_mfma_f32_16x16x32_bf16 v[52:55], v[172:175], v[180:183], v[52:55]
	v_mfma_f32_16x16x32_bf16 v[40:43], v[164:167], v[188:191], v[40:43]
	v_mfma_f32_16x16x32_bf16 v[36:39], v[172:175], v[188:191], v[36:39]
	v_mfma_f32_16x16x32_bf16 v[24:27], v[164:167], v[196:199], v[24:27]
	v_mfma_f32_16x16x32_bf16 v[20:23], v[172:175], v[196:199], v[20:23]
	v_mfma_f32_16x16x32_bf16 v[8:11], v[164:167], v[208:211], v[8:11]
	v_mfma_f32_16x16x32_bf16 v[4:7], v[172:175], v[208:211], v[4:7]

	s_barrier
	s_add_i32 s81, 0, 0x18000
	s_add_i32 s82, 0, 0x1c000
	v_add_u32_e32 v156, s81, v149
	v_add_u32_e32 v172, s82, v149
	ds_read_b128 v[140:143], v156
	ds_read_b128 v[144:147], v156 offset:1024
	ds_read_b128 v[152:155], v156 offset:2048
	ds_read_b128 v[156:159], v156 offset:3072
	ds_read_b128 v[160:163], v172
	ds_read_b128 v[164:167], v172 offset:1024
	ds_read_b128 v[168:171], v172 offset:2048
	ds_read_b128 v[172:175], v172 offset:3072
	s_add_u32 s50, s50, 0x80000
	s_addc_u32 s51, s51, 0
	s_mov_b32 m0, s59
	s_nop 0
	global_load_lds_dwordx4 v[214:215], off
	s_mov_b32 m0, s60
	s_nop 0
	global_load_lds_dwordx4 v[216:217], off
	s_mov_b32 m0, s61
	v_lshl_add_u64 v[218:219], s[50:51], 0, v[134:135]
	ds_read_b128 v[176:179], v151 offset:32768
	ds_read_b128 v[180:183], v151 offset:33792
	ds_read_b128 v[184:187], v151 offset:34816
	ds_read_b128 v[188:191], v151 offset:35840
	ds_read_b128 v[192:195], v151 offset:36864
	ds_read_b128 v[196:199], v151 offset:37888
	ds_read_b128 v[204:207], v151 offset:38912
	ds_read_b128 v[208:211], v151 offset:39936
	global_load_lds_dwordx4 v[218:219], off
	v_lshl_add_u64 v[218:219], s[50:51], 0, v[132:133]
	s_mov_b32 m0, s70
	s_nop 0
	global_load_lds_dwordx4 v[218:219], off
	s_waitcnt vmcnt(8)
	s_waitcnt lgkmcnt(0)
	s_barrier

	s_waitcnt lgkmcnt(0)
	v_mfma_f32_16x16x32_bf16 v[128:131], v[140:143], v[176:179], v[128:131]
	v_mfma_f32_16x16x32_bf16 v[124:127], v[152:155], v[176:179], v[124:127]
	v_mfma_f32_16x16x32_bf16 v[112:115], v[140:143], v[184:187], v[112:115]
	v_mfma_f32_16x16x32_bf16 v[108:111], v[152:155], v[184:187], v[108:111]
	v_mfma_f32_16x16x32_bf16 v[96:99], v[140:143], v[192:195], v[96:99]
	v_mfma_f32_16x16x32_bf16 v[92:95], v[152:155], v[192:195], v[92:95]
	v_mfma_f32_16x16x32_bf16 v[80:83], v[140:143], v[204:207], v[80:83]
	v_mfma_f32_16x16x32_bf16 v[76:79], v[152:155], v[204:207], v[76:79]
	v_mfma_f32_16x16x32_bf16 v[128:131], v[144:147], v[180:183], v[128:131]
	v_mfma_f32_16x16x32_bf16 v[124:127], v[156:159], v[180:183], v[124:127]
	v_mfma_f32_16x16x32_bf16 v[112:115], v[144:147], v[188:191], v[112:115]
	v_mfma_f32_16x16x32_bf16 v[108:111], v[156:159], v[188:191], v[108:111]
	v_mfma_f32_16x16x32_bf16 v[96:99], v[144:147], v[196:199], v[96:99]
	v_mfma_f32_16x16x32_bf16 v[92:95], v[156:159], v[196:199], v[92:95]
	v_mfma_f32_16x16x32_bf16 v[80:83], v[144:147], v[208:211], v[80:83]
	v_mfma_f32_16x16x32_bf16 v[76:79], v[156:159], v[208:211], v[76:79]


	v_mfma_f32_16x16x32_bf16 v[120:123], v[160:163], v[176:179], v[120:123]
	v_mfma_f32_16x16x32_bf16 v[116:119], v[168:171], v[176:179], v[116:119]
	v_mfma_f32_16x16x32_bf16 v[104:107], v[160:163], v[184:187], v[104:107]
	v_mfma_f32_16x16x32_bf16 v[100:103], v[168:171], v[184:187], v[100:103]
	v_mfma_f32_16x16x32_bf16 v[88:91], v[160:163], v[192:195], v[88:91]
	v_mfma_f32_16x16x32_bf16 v[84:87], v[168:171], v[192:195], v[84:87]
	v_mfma_f32_16x16x32_bf16 v[72:75], v[160:163], v[204:207], v[72:75]
	v_mfma_f32_16x16x32_bf16 v[68:71], v[168:171], v[204:207], v[68:71]
	v_mfma_f32_16x16x32_bf16 v[120:123], v[164:167], v[180:183], v[120:123]
	v_mfma_f32_16x16x32_bf16 v[116:119], v[172:175], v[180:183], v[116:119]
	v_mfma_f32_16x16x32_bf16 v[104:107], v[164:167], v[188:191], v[104:107]
	v_mfma_f32_16x16x32_bf16 v[100:103], v[172:175], v[188:191], v[100:103]
	v_mfma_f32_16x16x32_bf16 v[88:91], v[164:167], v[196:199], v[88:91]
	v_mfma_f32_16x16x32_bf16 v[84:87], v[172:175], v[196:199], v[84:87]
	v_mfma_f32_16x16x32_bf16 v[72:75], v[164:167], v[208:211], v[72:75]
	v_mfma_f32_16x16x32_bf16 v[68:71], v[172:175], v[208:211], v[68:71]

	s_barrier
	s_add_i32 s50, s81, s52
	v_lshl_add_u64 v[200:201], v[200:201], 0, s[12:13]
	s_mov_b32 m0, s50
	ds_read_b128 v[176:179], v151 offset:49152
	ds_read_b128 v[180:183], v151 offset:50176
	ds_read_b128 v[184:187], v151 offset:51200
	ds_read_b128 v[188:191], v151 offset:52224
	ds_read_b128 v[192:195], v151 offset:53248
	ds_read_b128 v[196:199], v151 offset:54272
	ds_read_b128 v[204:207], v151 offset:55296
	ds_read_b128 v[208:211], v151 offset:56320
	global_load_lds_dwordx4 v[200:201], off
	s_add_i32 m0, s50, 0x2000
	s_add_u32 s48, s48, 0x80080
	v_lshl_add_u64 v[200:201], v[212:213], 0, s[12:13]
	s_addc_u32 s49, s49, 0
	s_add_i32 s50, s82, s52
	global_load_lds_dwordx4 v[200:201], off
	v_lshl_add_u64 v[200:201], s[48:49], 0, v[2:3]
	s_mov_b32 m0, s50
	s_nop 0
	global_load_lds_dwordx4 v[200:201], off
	v_lshl_add_u64 v[200:201], s[48:49], 0, v[0:1]
	s_add_i32 m0, s50, 0x2000
	s_nop 0
	global_load_lds_dwordx4 v[200:201], off


	s_waitcnt vmcnt(6)
	s_waitcnt lgkmcnt(0)
	s_barrier

	s_waitcnt lgkmcnt(0)
	v_mfma_f32_16x16x32_bf16 v[64:67], v[140:143], v[176:179], v[64:67]
	v_mfma_f32_16x16x32_bf16 v[60:63], v[152:155], v[176:179], v[60:63]
	v_mfma_f32_16x16x32_bf16 v[48:51], v[140:143], v[184:187], v[48:51]
	v_mfma_f32_16x16x32_bf16 v[44:47], v[152:155], v[184:187], v[44:47]
	v_mfma_f32_16x16x32_bf16 v[32:35], v[140:143], v[192:195], v[32:35]
	v_mfma_f32_16x16x32_bf16 v[28:31], v[152:155], v[192:195], v[28:31]
	v_mfma_f32_16x16x32_bf16 v[16:19], v[140:143], v[204:207], v[16:19]
	v_mfma_f32_16x16x32_bf16 v[12:15], v[152:155], v[204:207], v[12:15]
	v_mfma_f32_16x16x32_bf16 v[64:67], v[144:147], v[180:183], v[64:67]
	v_mfma_f32_16x16x32_bf16 v[60:63], v[156:159], v[180:183], v[60:63]
	v_mfma_f32_16x16x32_bf16 v[48:51], v[144:147], v[188:191], v[48:51]
	v_mfma_f32_16x16x32_bf16 v[44:47], v[156:159], v[188:191], v[44:47]
	v_mfma_f32_16x16x32_bf16 v[32:35], v[144:147], v[196:199], v[32:35]
	v_mfma_f32_16x16x32_bf16 v[28:31], v[156:159], v[196:199], v[28:31]
	v_mfma_f32_16x16x32_bf16 v[16:19], v[144:147], v[208:211], v[16:19]
	v_mfma_f32_16x16x32_bf16 v[12:15], v[156:159], v[208:211], v[12:15]


	v_mfma_f32_16x16x32_bf16 v[56:59], v[160:163], v[176:179], v[56:59]
	v_mfma_f32_16x16x32_bf16 v[52:55], v[168:171], v[176:179], v[52:55]
	v_mfma_f32_16x16x32_bf16 v[40:43], v[160:163], v[184:187], v[40:43]
	v_mfma_f32_16x16x32_bf16 v[36:39], v[168:171], v[184:187], v[36:39]
	v_mfma_f32_16x16x32_bf16 v[24:27], v[160:163], v[192:195], v[24:27]
	v_mfma_f32_16x16x32_bf16 v[20:23], v[168:171], v[192:195], v[20:23]
	v_mfma_f32_16x16x32_bf16 v[8:11], v[160:163], v[204:207], v[8:11]
	v_mfma_f32_16x16x32_bf16 v[4:7], v[168:171], v[204:207], v[4:7]
	v_mfma_f32_16x16x32_bf16 v[56:59], v[164:167], v[180:183], v[56:59]
	v_mfma_f32_16x16x32_bf16 v[52:55], v[172:175], v[180:183], v[52:55]
	v_mfma_f32_16x16x32_bf16 v[40:43], v[164:167], v[188:191], v[40:43]
	v_mfma_f32_16x16x32_bf16 v[36:39], v[172:175], v[188:191], v[36:39]
	v_mfma_f32_16x16x32_bf16 v[24:27], v[164:167], v[196:199], v[24:27]
	v_mfma_f32_16x16x32_bf16 v[20:23], v[172:175], v[196:199], v[20:23]
	v_mfma_f32_16x16x32_bf16 v[8:11], v[164:167], v[208:211], v[8:11]
	v_mfma_f32_16x16x32_bf16 v[4:7], v[172:175], v[208:211], v[4:7]

	s_add_i32 s80, s80, 2
	s_add_u32 s46, s46, 0x100
	s_addc_u32 s47, s47, 0
	s_add_u32 s78, s78, 0x100
	s_addc_u32 s79, s79, 0
	s_add_u32 s48, s46, 0xfff80080
	s_addc_u32 s49, s47, -1
	s_add_i32 s81, 0, 0x10000
	s_cmp_eq_u32 s80, 28
	s_cselect_b32 s51, s35, s49
	s_cselect_b32 s50, s76, s48
	s_cselect_b32 s49, s21, s79
	s_cselect_b32 s48, s77, s78
	s_add_i32 s84, 0, 0x14000
	s_cmp_gt_u32 s80, 29
	s_barrier
	s_cbranch_scc0 .Lk2_rot


	v_readlane_b32 s78, v254, 48
	v_readlane_b32 s80, v254, 50
	s_and_b64 vcc, exec, s[10:11]
	v_readlane_b32 s79, v254, 49
	v_readlane_b32 s81, v254, 51
	v_readlane_b32 s76, v254, 62
	v_readlane_b32 s77, v254, 63
	s_cbranch_vccz .LBB0_688
	s_barrier
